# attn v6: ping-pong + no permlane (V rows DMA order) + 16-row K swizzle, double-buffered K
# speedup vs baseline: 1.0730x; 1.0048x over previous
; #define SBAR() __builtin_amdgcn_sched_barrier(0)
; template <int MODE>
; __device__ __forceinline__ void attn_unit(const UnitArgs& A, char* lds, const int wave_) {
;     ...
;     float l_reg = 0; f32x16 o[4] = {}; bf16x8 qr[4];
;     { const bf16_t* Qw = A.Qb + (long)(qb * QBLK + r32) * NZ + half * 64 + hi * 8;
; #pragma unroll
;       for (int d0 = 0; d0 < 4; ++d0) qr[d0] = *reinterpret_cast<const bf16x8*>(Qw + d0 * 16); }
;     const int sr = tid >> 4, sc = (tid & 15) * 8, vst0 = v_st(sr, sc);
;     const int vbase = (int)(uintptr_t)V_lds + v_rd_base(lane) + (MODE == 0 ? 0 : half * 1024);
;     const int ldk = A.ldk; const unsigned ldoff = (unsigned)(sr * ldk + sc) * 2u;
;     struct { bf16x8 vs0, vs1; } sr_[1];
;     const unsigned kdoff = (unsigned)(sr * ldk + (((tid & 15) ^ (sr & 7)) * 8)) * 2u;
;     const unsigned kdst0 = (unsigned)__builtin_amdgcn_readfirstlane((int)((unsigned)(uintptr_t)K_lds + (unsigned)wid * 1024u));
;     ...
;     auto zone_of = [&](int t) -> int { const int k0 = 64 * t, qw0 = A.q0 + 32 * qb; return (k0 + 63 - qw0 <= -128) ? 0 : ((k0 - qw0 - 31 >= 128) ? 2 : 1); };
;     ...
;     auto post = [&](f32x16& p0, f32x16& p1, int t) {
;         SBAR();
;         if (MODE == 0) {
;             if (zone_of(t) == 1) { const int k0 = 64 * t, qw0 = A.q0 + 32 * qb;
;                 const float* b = lutA + A.h * LUTA_STRIDE + (k0 - qw0 - r32 + 4 * hi + 320);
; #pragma unroll
;                 for (int r = 0; r < 16; ++r) { const int c = (r & 3) + 8 * (r >> 2); p0[r] += b[c]; p1[r] += b[32 + c]; } }
;         } else if (MODE == 1) {
;             const int kr = A.tile0 + t, rq = A.q0 + (qb >> 1);
;             int rs = rq - 4; rs = rs < 0 ? 0 : rs; rs = rs > A.R - 8 ? A.R - 8 : rs;
;             if (kr < rs || kr >= rs + 8) {
; #pragma unroll
;                 for (int r = 0; r < 16; ++r) { p0[r] = NEG; p1[r] = NEG; }
;             } else {
;                 const int c = 32 * (qb & 1) + r32; int cs = c - 8; cs = cs < 0 ? 0 : cs; cs = cs > 48 ? 48 : cs;
;                 const float* b = lutB + ((2 * A.h + half) * 15 + (kr - rq + 7)) * 128 + 64 + 4 * hi - c;
; #pragma unroll
;                 for (int r = 0; r < 16; ++r) { const int cc = (r & 3) + 8 * (r >> 2), j = 4 * hi + cc;
;                     p0[r] = ((unsigned)(j - cs) < 16u) ? p0[r] + b[cc] : NEG; p1[r] = ((unsigned)(j + 32 - cs) < 16u) ? p1[r] + b[32 + cc] : NEG; } }
;         }
;         SBAR();
;     };
.LBB0_314:
	s_add_i32 s84, s8, s7
	s_mul_i32 s3, s84, 0x1400
	s_mul_hi_u32 s2, s84, 0x1400
	s_add_u32 s17, s37, s3
	s_addc_u32 s18, s38, s2
	s_lshl_b32 s2, s6, 7
	s_ashr_i32 s3, s2, 31
	s_lshl_b64 s[2:3], s[2:3], 1
	s_add_u32 s24, s17, s2
	s_addc_u32 s25, s18, s3
	s_mul_i32 s31, s7, 0x1400
	s_mul_hi_u32 s30, s7, 0x1400
	s_add_u32 s6, s37, s31
	s_addc_u32 s7, s38, s30
	s_add_u32 s6, s6, s2
	s_addc_u32 s7, s7, s3
	s_and_b32 s18, s1, 3
	v_and_b32_e32 v156, 31, v40
	s_lshl_b32 s28, s18, 5
	v_or_b32_e32 v0, s28, v156
	s_ashr_i32 s17, s0, 8
	v_mul_u32_u24_e32 v144, 0x1400, v0
	v_lshl_add_u64 v[0:1], s[24:25], 0, v[144:145]
	s_lshl_b32 s24, s17, 6
	v_bfe_u32 v157, v40, 5, 1
	s_ashr_i32 s25, s24, 31
	v_lshl_add_u64 v[0:1], s[24:25], 1, v[0:1]
	v_lshlrev_b32_e32 v136, 4, v157
	v_mov_b32_e32 v137, v145
	v_lshl_add_u64 v[0:1], v[0:1], 0, v[136:137]
	global_load_dwordx4 v[108:111], v[0:1], off
	global_load_dwordx4 v[104:107], v[0:1], off offset:32
	global_load_dwordx4 v[100:103], v[0:1], off offset:64
	global_load_dwordx4 v[96:99], v[0:1], off offset:96
	s_add_u32 s24, s6, 0x400
	s_addc_u32 s25, s7, 0
	s_add_u32 s26, s6, 0x800
	s_addc_u32 s27, s7, 0
	v_and_b32_e32 v137, 63, v40
	v_lshlrev_b32_e32 v176, 8, v156
	v_and_b32_e32 v178, 15, v156
	v_lshlrev_b32_e32 v178, 4, v178
	s_lshl_b32 s99, s17, 7
	v_or_b32_e32 v179, s99, v136
	v_xor_b32_e32 v179, v179, v178
	v_add_u32_e32 v176, v176, v179
	v_add_u32_e32 v164, 0x8000, v176
	v_xor_b32_e32 v165, 32, v164
	v_xor_b32_e32 v166, 64, v164
	v_xor_b32_e32 v167, 0x60, v164
	v_and_b32_e32 v176, 3, v137
	v_lshlrev_b32_e32 v176, 3, v176
	v_bfe_u32 v178, v137, 2, 2
	v_lshlrev_b32_e32 v178, 6, v178
	v_bfe_u32 v179, v137, 4, 1
	v_lshlrev_b32_e32 v179, 5, v179
	v_bfe_u32 v180, v137, 5, 1
	v_lshlrev_b32_e32 v180, 8, v180
	v_or3_b32 v176, v176, v178, v179
	v_or_b32_e32 v168, v176, v180
	v_lshrrev_b32_e32 v176, 4, v40
	v_and_b32_e32 v178, 15, v40
	v_and_b32_e32 v179, 15, v176
	v_xor_b32_e32 v178, v178, v179
	v_lshlrev_b32_e32 v178, 4, v178
	v_mul_u32_u24_e32 v176, 0x1400, v176
	v_add_u32_e32 v169, v176, v178
	v_add_u32_e32 v170, 0x28000, v169
	v_bfe_u32 v178, v137, 2, 3
	s_bfe_u32 s99, s1, 0x10001
	s_lshl_b32 s99, s99, 3
	s_bfe_u32 s6, s1, 0x10002
	s_lshl_b32 s6, s6, 4
	s_or_b32 s99, s99, s6
	v_or_b32_e32 v178, s99, v178
	v_mul_u32_u24_e32 v178, 0x1400, v178
	s_and_b32 s99, s1, 1
	s_lshl_b32 s99, s99, 7
	v_bfe_u32 v176, v137, 5, 1
	v_lshlrev_b32_e32 v176, 6, v176
	v_and_b32_e32 v179, 3, v137
	v_lshlrev_b32_e32 v179, 4, v179
	v_add3_u32 v178, v178, v176, v179
	v_add_u32_e32 v171, s99, v178
	v_add_u32_e32 v172, 0x28000, v171
	s_lshl_b32 s33, s1, 10
	s_add_u32 s31, s33, 0x8000
	s_add_i32 s99, s8, s28
	s_sub_i32 s29, s99, 0xbf
	s_add_i32 s30, s99, 0x9f
	s_sub_i32 s35, 0x140, s99
	s_lshl_b32 s35, s35, 2
	s_add_i32 s35, s35, s19
	v_lshlrev_b32_e32 v176, 2, v157
	v_sub_u32_e32 v176, v176, v156
	v_lshlrev_b32_e32 v174, 2, v176
	v_mov_b32_e32 v176, s13
	v_sub_f32_e32 v178, s21, v176
	v_sub_f32_e32 v179, s20, v176
	s_xor_b32 s98, s13, 0x80000000
	s_sub_i32 s20, s22, 1
	v_readfirstlane_b32 s21, v178
	v_readfirstlane_b32 s22, v179
	s_mov_b32 s34, 0
	s_mov_b32 s23, 0
	s_cmp_le_i32 s23, s29
	s_cselect_b32 s9, s21, s98
	v_mov_b32_e32 v68, s9
	v_mov_b32_e32 v69, s9
	v_mov_b32_e32 v70, s9
	v_mov_b32_e32 v71, s9
	v_mov_b32_e32 v72, s9
	v_mov_b32_e32 v73, s9
	v_mov_b32_e32 v74, s9
	v_mov_b32_e32 v75, s9
	v_mov_b32_e32 v76, s9
	v_mov_b32_e32 v77, s9
	v_mov_b32_e32 v78, s9
	v_mov_b32_e32 v79, s9
	v_mov_b32_e32 v80, s9
	v_mov_b32_e32 v81, s9
	v_mov_b32_e32 v82, s9
	v_mov_b32_e32 v83, s9
	v_mov_b32_e32 v0, 0
	v_mov_b32_e32 v1, 0
	v_mov_b32_e32 v2, 0
	v_mov_b32_e32 v3, 0
	v_mov_b32_e32 v4, 0
	v_mov_b32_e32 v5, 0
	v_mov_b32_e32 v6, 0
	v_mov_b32_e32 v7, 0
	v_mov_b32_e32 v8, 0
	v_mov_b32_e32 v9, 0
	v_mov_b32_e32 v10, 0
	v_mov_b32_e32 v11, 0
	v_mov_b32_e32 v12, 0
	v_mov_b32_e32 v13, 0
	v_mov_b32_e32 v14, 0
	v_mov_b32_e32 v15, 0
	v_mov_b32_e32 v16, 0
	v_mov_b32_e32 v17, 0
	v_mov_b32_e32 v18, 0
	v_mov_b32_e32 v19, 0
	v_mov_b32_e32 v20, 0
	v_mov_b32_e32 v21, 0
	v_mov_b32_e32 v22, 0
	v_mov_b32_e32 v23, 0
	v_mov_b32_e32 v24, 0
	v_mov_b32_e32 v25, 0
	v_mov_b32_e32 v26, 0
	v_mov_b32_e32 v27, 0
	v_mov_b32_e32 v28, 0
	v_mov_b32_e32 v29, 0
	v_mov_b32_e32 v30, 0
	v_mov_b32_e32 v31, 0
	v_mov_b32_e32 v32, 0
	v_mov_b32_e32 v33, 0
	v_mov_b32_e32 v34, 0
	v_mov_b32_e32 v35, 0
	v_mov_b32_e32 v36, 0
	v_mov_b32_e32 v37, 0
	v_mov_b32_e32 v38, 0
	v_mov_b32_e32 v39, 0
	v_mov_b32_e32 v40, 0
	v_mov_b32_e32 v41, 0
	v_mov_b32_e32 v42, 0
	v_mov_b32_e32 v43, 0
	v_mov_b32_e32 v44, 0
	v_mov_b32_e32 v45, 0
	v_mov_b32_e32 v46, 0
	v_mov_b32_e32 v47, 0
	v_mov_b32_e32 v48, 0
	v_mov_b32_e32 v49, 0
	v_mov_b32_e32 v50, 0
	v_mov_b32_e32 v51, 0
	v_mov_b32_e32 v52, 0
	v_mov_b32_e32 v53, 0
	v_mov_b32_e32 v54, 0
	v_mov_b32_e32 v55, 0
	v_mov_b32_e32 v56, 0
	v_mov_b32_e32 v57, 0
	v_mov_b32_e32 v58, 0
	v_mov_b32_e32 v59, 0
	v_mov_b32_e32 v60, 0
	v_mov_b32_e32 v61, 0
	v_mov_b32_e32 v62, 0
	v_mov_b32_e32 v63, 0
	v_mov_b32_e32 v64, 0
	v_mov_b32_e32 v65, 0
	v_mov_b32_e32 v66, 0
	v_mov_b32_e32 v67, 0
	v_mov_b32_e32 v178, 0
	v_mov_b32_e32 v179, 0
	v_mov_b32_e32 v180, 0
	v_mov_b32_e32 v181, 0
	s_mov_b32 m0, s31
	s_add_u32 s99, s31, 0x2000
	global_load_lds_dwordx4 v169, s[24:25]
	s_mov_b32 m0, s99
	s_xor_b32 s31, s31, 0x4000
	global_load_lds_dwordx4 v170, s[24:25]
	s_add_u32 s24, s24, 0x50000
	s_addc_u32 s25, s25, 0
	s_mov_b32 m0, s31
	s_add_u32 s99, s31, 0x2000
	global_load_lds_dwordx4 v169, s[24:25]
	s_mov_b32 m0, s99
	s_xor_b32 s31, s31, 0x4000
	global_load_lds_dwordx4 v170, s[24:25]
	s_add_u32 s24, s24, 0x50000
	s_addc_u32 s25, s25, 0
	s_mov_b32 m0, s33
	s_add_u32 s99, s33, 0x2000
	global_load_lds_dwordx4 v171, s[26:27]
	s_mov_b32 m0, s99
	s_xor_b32 s33, s33, 0x4000
	global_load_lds_dwordx4 v172, s[26:27]
	s_add_u32 s26, s26, 0x50000
	s_addc_u32 s27, s27, 0
	s_waitcnt vmcnt(0)
	s_barrier
; #define SBAR() __builtin_amdgcn_sched_barrier(0)
; #define KFRAG(d0, row) (*reinterpret_cast<const bf16x8*>(Ks + KSWZ((row), (half * 64 + (d0) * 16 + hi * 8) * 2)))
; __device__ __forceinline__ void expHalf(f32x16& p0) {
; #pragma unroll
;     for (int r = 0; r < 16; ++r) p0[r] = __builtin_amdgcn_exp2f(p0[r]);
; }
; __device__ __forceinline__ void finishSM(f32x16& p0, f32x16& p1, float& l_reg, bf16x8& pa0, bf16x8& pa1, bf16x8& pa2, bf16x8& pa3) {
;     float ps = 0;
; #pragma unroll
;     for (int r = 0; r < 16; ++r) ps += p0[r];
; #pragma unroll
;     for (int r = 0; r < 16; ++r) ps += p1[r];
;     l_reg += ps;
;     ...
;     PK4(p0, 0, pa0); PK4(p0, 8, pa1); PK4(p1, 0, pa2); PK4(p1, 8, pa3);
;     ...
; }
; __device__ __forceinline__ void qkt(f32x16& p0, f32x16& p1, const char* Ks, const bf16x8* qr, float c0, int r32, int hi, int half) {
;     ...
;     bf16x8 a0 = KFRAG(0, r32), a1 = KFRAG(0, 32 + r32), b0 = KFRAG(1, r32), b1 = KFRAG(1, 32 + r32);
;     SBAR();
; #pragma unroll
;     for (int r = 0; r < 16; ++r) { p0[r] = c0; p1[r] = c0; }
;     SBAR();
;     p0 = __builtin_amdgcn_mfma_f32_32x32x16_bf16(a0, qr[0], p0, 0, 0, 0); p1 = __builtin_amdgcn_mfma_f32_32x32x16_bf16(a1, qr[0], p1, 0, 0, 0);
;     a0 = KFRAG(2, r32); a1 = KFRAG(2, 32 + r32);
;     SBAR();
;     p0 = __builtin_amdgcn_mfma_f32_32x32x16_bf16(b0, qr[1], p0, 0, 0, 0); p1 = __builtin_amdgcn_mfma_f32_32x32x16_bf16(b1, qr[1], p1, 0, 0, 0);
;     b0 = KFRAG(3, r32); b1 = KFRAG(3, 32 + r32);
;     SBAR();
;     p0 = __builtin_amdgcn_mfma_f32_32x32x16_bf16(a0, qr[2], p0, 0, 0, 0); p1 = __builtin_amdgcn_mfma_f32_32x32x16_bf16(a1, qr[2], p1, 0, 0, 0);
;     p0 = __builtin_amdgcn_mfma_f32_32x32x16_bf16(b0, qr[3], p0, 0, 0, 0); p1 = __builtin_amdgcn_mfma_f32_32x32x16_bf16(b1, qr[3], p1, 0, 0, 0);
; template <int MODE>
; __device__ __forceinline__ void attn_unit(const UnitArgs& A, char* lds, const int wave_) {
;     ...
;     auto post = [&](f32x16& p0, f32x16& p1, int t) {
;         SBAR();
;         if (MODE == 0) {
;             if (zone_of(t) == 1) { const int k0 = 64 * t, qw0 = A.q0 + 32 * qb;
;                 const float* b = lutA + A.h * LUTA_STRIDE + (k0 - qw0 - r32 + 4 * hi + 320);
; #pragma unroll
;                 for (int r = 0; r < 16; ++r) { const int c = (r & 3) + 8 * (r >> 2); p0[r] += b[c]; p1[r] += b[32 + c]; } }
	s_cmp_lg_u32 s17, 0
	s_cbranch_scc1 .Lat_g1
	s_setprio 0
	ds_read_b128 v[224:227], v164
	ds_read_b128 v[228:231], v164 offset:8192
	ds_read_b128 v[232:235], v165
	ds_read_b128 v[236:239], v165 offset:8192
	ds_read_b128 v[240:243], v166
	ds_read_b128 v[244:247], v166 offset:8192
	ds_read_b128 v[248:251], v167
	ds_read_b128 v[188:191], v167 offset:8192
	v_xor_b32_e32 v164, 0x4000, v164
	v_xor_b32_e32 v165, 0x4000, v165
	v_xor_b32_e32 v166, 0x4000, v166
	v_xor_b32_e32 v167, 0x4000, v167
	s_waitcnt lgkmcnt(7)
	v_mfma_f32_32x32x16_bf16 v[112:127], v[224:227], v[108:111], v[68:83]
	s_waitcnt lgkmcnt(6)
	v_mfma_f32_32x32x16_bf16 v[192:207], v[228:231], v[108:111], v[68:83]
	s_waitcnt lgkmcnt(5)
	v_mfma_f32_32x32x16_bf16 v[112:127], v[232:235], v[104:107], v[112:127]
	s_waitcnt lgkmcnt(4)
	v_mfma_f32_32x32x16_bf16 v[192:207], v[236:239], v[104:107], v[192:207]
	s_waitcnt lgkmcnt(3)
	v_mfma_f32_32x32x16_bf16 v[112:127], v[240:243], v[100:103], v[112:127]
	s_waitcnt lgkmcnt(2)
	v_mfma_f32_32x32x16_bf16 v[192:207], v[244:247], v[100:103], v[192:207]
	s_waitcnt lgkmcnt(1)
	v_mfma_f32_32x32x16_bf16 v[112:127], v[248:251], v[96:99], v[112:127]
	s_waitcnt lgkmcnt(0)
	v_mfma_f32_32x32x16_bf16 v[192:207], v[188:191], v[96:99], v[192:207]
	s_nop 7
	s_nop 3
	s_barrier
.Lat_g0_loop:
	s_setprio 1
	s_cmp_gt_i32 s23, s29
	s_cselect_b32 s99, 1, 0
	s_cmp_lt_i32 s23, s30
	s_cselect_b32 s6, 1, 0
	s_and_b32 s99, s99, s6
	s_cbranch_scc0 .Lat_far_g0l
	v_add_u32_e32 v186, s35, v174
	ds_read2_b32 v[224:225], v186 offset0:0 offset1:1
	ds_read2_b32 v[226:227], v186 offset0:2 offset1:3
	ds_read2_b32 v[228:229], v186 offset0:8 offset1:9
	ds_read2_b32 v[230:231], v186 offset0:10 offset1:11
	ds_read2_b32 v[232:233], v186 offset0:16 offset1:17
	ds_read2_b32 v[234:235], v186 offset0:18 offset1:19
	ds_read2_b32 v[236:237], v186 offset0:24 offset1:25
	ds_read2_b32 v[238:239], v186 offset0:26 offset1:27
	s_waitcnt lgkmcnt(4)
	ds_read2_b32 v[240:241], v186 offset0:32 offset1:33
	ds_read2_b32 v[242:243], v186 offset0:34 offset1:35
	ds_read2_b32 v[244:245], v186 offset0:40 offset1:41
	ds_read2_b32 v[246:247], v186 offset0:42 offset1:43
	ds_read2_b32 v[248:249], v186 offset0:48 offset1:49
	ds_read2_b32 v[250:251], v186 offset0:50 offset1:51
	ds_read2_b32 v[188:189], v186 offset0:56 offset1:57
	ds_read2_b32 v[190:191], v186 offset0:58 offset1:59
	s_waitcnt lgkmcnt(8)
	v_add_f32_e32 v112, v112, v224
	v_add_f32_e32 v113, v113, v225
	v_add_f32_e32 v114, v114, v226
	v_add_f32_e32 v115, v115, v227
	v_add_f32_e32 v116, v116, v228
	v_add_f32_e32 v117, v117, v229
	v_add_f32_e32 v118, v118, v230
	v_add_f32_e32 v119, v119, v231
	v_add_f32_e32 v120, v120, v232
	v_add_f32_e32 v121, v121, v233
	v_add_f32_e32 v122, v122, v234
	v_add_f32_e32 v123, v123, v235
	v_add_f32_e32 v124, v124, v236
	v_add_f32_e32 v125, v125, v237
	v_add_f32_e32 v126, v126, v238
	v_add_f32_e32 v127, v127, v239
	s_waitcnt lgkmcnt(0)
	v_add_f32_e32 v192, v192, v240
	v_add_f32_e32 v193, v193, v241
	v_add_f32_e32 v194, v194, v242
	v_add_f32_e32 v195, v195, v243
	v_add_f32_e32 v196, v196, v244
	v_add_f32_e32 v197, v197, v245
	v_add_f32_e32 v198, v198, v246
	v_add_f32_e32 v199, v199, v247
	v_add_f32_e32 v200, v200, v248
	v_add_f32_e32 v201, v201, v249
	v_add_f32_e32 v202, v202, v250
	v_add_f32_e32 v203, v203, v251
	v_add_f32_e32 v204, v204, v188
	v_add_f32_e32 v205, v205, v189
	v_add_f32_e32 v206, v206, v190
	v_add_f32_e32 v207, v207, v191
.Lat_far_g0l:
	v_exp_f32_e32 v112, v112
	v_exp_f32_e32 v113, v113
	v_exp_f32_e32 v114, v114
	v_exp_f32_e32 v115, v115
	v_exp_f32_e32 v116, v116
	v_exp_f32_e32 v117, v117
	v_exp_f32_e32 v118, v118
	v_exp_f32_e32 v119, v119
	v_exp_f32_e32 v120, v120
	v_exp_f32_e32 v121, v121
	v_exp_f32_e32 v122, v122
	v_exp_f32_e32 v123, v123
	v_exp_f32_e32 v124, v124
	v_exp_f32_e32 v125, v125
	v_exp_f32_e32 v126, v126
	v_exp_f32_e32 v127, v127
	v_exp_f32_e32 v192, v192
	v_add_f32_e32 v64, v64, v112
	v_exp_f32_e32 v193, v193
	v_add_f32_e32 v65, v65, v113
	v_exp_f32_e32 v194, v194
	v_add_f32_e32 v66, v66, v114
	v_exp_f32_e32 v195, v195
	v_add_f32_e32 v67, v67, v115
	v_exp_f32_e32 v196, v196
	v_add_f32_e32 v64, v64, v116
	v_exp_f32_e32 v197, v197
	v_add_f32_e32 v65, v65, v117
	v_exp_f32_e32 v198, v198
	v_add_f32_e32 v66, v66, v118
	v_exp_f32_e32 v199, v199
	v_add_f32_e32 v67, v67, v119
	v_exp_f32_e32 v200, v200
	v_add_f32_e32 v64, v64, v120
	v_exp_f32_e32 v201, v201
	v_add_f32_e32 v65, v65, v121
	v_exp_f32_e32 v202, v202
	v_add_f32_e32 v66, v66, v122
	v_exp_f32_e32 v203, v203
	v_add_f32_e32 v67, v67, v123
	v_exp_f32_e32 v204, v204
	v_add_f32_e32 v64, v64, v124
	v_exp_f32_e32 v205, v205
	v_add_f32_e32 v65, v65, v125
	v_exp_f32_e32 v206, v206
	v_add_f32_e32 v66, v66, v126
	v_exp_f32_e32 v207, v207
	v_add_f32_e32 v67, v67, v127
	v_cvt_pk_bf16_f32 v208, v112, v113
	v_cvt_pk_bf16_f32 v209, v114, v115
	v_cvt_pk_bf16_f32 v210, v116, v117
	v_cvt_pk_bf16_f32 v211, v118, v119
	v_cvt_pk_bf16_f32 v212, v120, v121
	v_cvt_pk_bf16_f32 v213, v122, v123
	v_cvt_pk_bf16_f32 v214, v124, v125
	v_cvt_pk_bf16_f32 v215, v126, v127
	v_add_f32_e32 v64, v64, v192
	v_add_f32_e32 v65, v65, v193
	v_add_f32_e32 v66, v66, v194
	v_add_f32_e32 v67, v67, v195
	v_add_f32_e32 v64, v64, v196
	v_add_f32_e32 v65, v65, v197
	v_add_f32_e32 v66, v66, v198
	v_add_f32_e32 v67, v67, v199
	v_add_f32_e32 v64, v64, v200
	v_add_f32_e32 v65, v65, v201
	v_add_f32_e32 v66, v66, v202
	v_add_f32_e32 v67, v67, v203
	v_add_f32_e32 v64, v64, v204
	v_add_f32_e32 v65, v65, v205
	v_add_f32_e32 v66, v66, v206
	v_add_f32_e32 v67, v67, v207
	v_cvt_pk_bf16_f32 v216, v192, v193
	v_cvt_pk_bf16_f32 v217, v194, v195
	v_cvt_pk_bf16_f32 v218, v196, v197
	v_cvt_pk_bf16_f32 v219, v198, v199
	v_cvt_pk_bf16_f32 v220, v200, v201
	v_cvt_pk_bf16_f32 v221, v202, v203
	v_cvt_pk_bf16_f32 v222, v204, v205
	v_cvt_pk_bf16_f32 v223, v206, v207
	s_add_i32 s99, s23, 64
	s_cmp_ge_i32 s99, s30
	s_cselect_b32 s6, s22, s98
	s_cmp_le_i32 s99, s29
	s_cselect_b32 s6, s21, s6
	s_nop 0
	s_cmp_lg_u32 s6, s9
	s_cbranch_scc0 .Lat_c0same_g0l
	s_mov_b32 s9, s6
	v_mov_b32_e32 v68, s9
	v_mov_b32_e32 v69, s9
	v_mov_b32_e32 v70, s9
	v_mov_b32_e32 v71, s9
	v_mov_b32_e32 v72, s9
	v_mov_b32_e32 v73, s9
	v_mov_b32_e32 v74, s9
	v_mov_b32_e32 v75, s9
	v_mov_b32_e32 v76, s9
	v_mov_b32_e32 v77, s9
	v_mov_b32_e32 v78, s9
	v_mov_b32_e32 v79, s9
	v_mov_b32_e32 v80, s9
	v_mov_b32_e32 v81, s9
	v_mov_b32_e32 v82, s9
	v_mov_b32_e32 v83, s9
; #define SBAR() __builtin_amdgcn_sched_barrier(0)
; __device__ __forceinline__ void qkt(f32x16& p0, f32x16& p1, const char* Ks, const bf16x8* qr, float c0, int r32, int hi, int half) {
;     ...
;     bf16x8 a0 = KFRAG(0, r32), a1 = KFRAG(0, 32 + r32), b0 = KFRAG(1, r32), b1 = KFRAG(1, 32 + r32);
;     SBAR();
; #pragma unroll
;     for (int r = 0; r < 16; ++r) { p0[r] = c0; p1[r] = c0; }
;     SBAR();
;     p0 = __builtin_amdgcn_mfma_f32_32x32x16_bf16(a0, qr[0], p0, 0, 0, 0); p1 = __builtin_amdgcn_mfma_f32_32x32x16_bf16(a1, qr[0], p1, 0, 0, 0);
;     a0 = KFRAG(2, r32); a1 = KFRAG(2, 32 + r32);
;     SBAR();
;     p0 = __builtin_amdgcn_mfma_f32_32x32x16_bf16(b0, qr[1], p0, 0, 0, 0); p1 = __builtin_amdgcn_mfma_f32_32x32x16_bf16(b1, qr[1], p1, 0, 0, 0);
;     b0 = KFRAG(3, r32); b1 = KFRAG(3, 32 + r32);
;     SBAR();
;     p0 = __builtin_amdgcn_mfma_f32_32x32x16_bf16(a0, qr[2], p0, 0, 0, 0); p1 = __builtin_amdgcn_mfma_f32_32x32x16_bf16(a1, qr[2], p1, 0, 0, 0);
;     p0 = __builtin_amdgcn_mfma_f32_32x32x16_bf16(b0, qr[3], p0, 0, 0, 0); p1 = __builtin_amdgcn_mfma_f32_32x32x16_bf16(b1, qr[3], p1, 0, 0, 0);
;     ...
; }
; __device__ __forceinline__ int v_st(int k, int c) { const int kk = (k & ~0xC) | ((k & 4) << 1) | ((k & 8) >> 1); return ((kk >> 3) * 4 + (c >> 5)) * 512 + ((kk & 7) * 32 + (c & 31)) * 2; }
; __device__ __forceinline__ int v_rd_base(int lane) { return ((lane & 3) << 3) | (((lane >> 2) & 3) << 6) | (((lane >> 4) & 1) << 5) | (((lane >> 5) & 1) << 8); }
; template <int OFF> __device__ __forceinline__ s16x4 tr_read(int vb) { s16x4 r; asm volatile("ds_read_b64_tr_b16 %0, %1 offset:%2" : "=&v"(r) : "v"(vb), "i"(OFF) : "memory"); return r; }
; template <int NB> __device__ __forceinline__ void pv_blocks(f32x16* o, int vb, bf16x8 pa0, bf16x8 pa1, bf16x8 pa2, bf16x8 pa3, f32x16& pe0, f32x16& pe1) {
;     s16x4 x[8], y[8];
;     ...
;     PVLOAD(0, x); PVWAIT();
;     if (NB == 4) {
;         PVLOAD(1, y); SBAR(); PVMMA(o[0], x); PVEXP(pe0, 0, 8); SBAR(); PVWAIT();
;         PVLOAD(2, x); SBAR(); PVMMA(o[1], y); PVEXP(pe0, 8, 8); SBAR(); PVWAIT();
;         PVLOAD(3, y); SBAR(); PVMMA(o[2], x); PVEXP(pe1, 0, 8); SBAR(); PVWAIT();
;         PVMMA(o[3], y); PVEXP(pe1, 8, 8);
;     } else {
;         PVLOAD(1, y); SBAR(); PVMMA(o[0], x); PVEXP(pe0, 0, 16); SBAR(); PVWAIT();
;         PVMMA(o[1], y); PVEXP(pe1, 0, 16);
;     }
;     ...
; }
.Lat_c0same_g0l:
	s_waitcnt vmcnt(0)
	s_barrier
	s_setprio 0
	ds_read_b128 v[224:227], v164
	ds_read_b128 v[228:231], v164 offset:8192
	ds_read_b128 v[232:235], v165
	ds_read_b128 v[236:239], v165 offset:8192
	ds_read_b128 v[240:243], v166
	ds_read_b128 v[244:247], v166 offset:8192
	ds_read_b128 v[248:251], v167
	ds_read_b128 v[188:191], v167 offset:8192
	v_xor_b32_e32 v164, 0x4000, v164
	v_xor_b32_e32 v165, 0x4000, v165
	v_xor_b32_e32 v166, 0x4000, v166
	v_xor_b32_e32 v167, 0x4000, v167
	s_waitcnt lgkmcnt(7)
	v_mfma_f32_32x32x16_bf16 v[112:127], v[224:227], v[108:111], v[68:83]
	s_waitcnt lgkmcnt(6)
	v_mfma_f32_32x32x16_bf16 v[192:207], v[228:231], v[108:111], v[68:83]
	ds_read_b64_tr_b16 v[84:85], v168 offset:0
	ds_read_b64_tr_b16 v[86:87], v168 offset:2048
	s_waitcnt lgkmcnt(7)
	v_mfma_f32_32x32x16_bf16 v[112:127], v[232:235], v[104:107], v[112:127]
	ds_read_b64_tr_b16 v[88:89], v168 offset:4096
	ds_read_b64_tr_b16 v[90:91], v168 offset:6144
	s_waitcnt lgkmcnt(8)
	v_mfma_f32_32x32x16_bf16 v[192:207], v[236:239], v[104:107], v[192:207]
	ds_read_b64_tr_b16 v[92:93], v168 offset:8192
	ds_read_b64_tr_b16 v[94:95], v168 offset:10240
	s_waitcnt lgkmcnt(9)
	v_mfma_f32_32x32x16_bf16 v[112:127], v[240:243], v[100:103], v[112:127]
	ds_read_b64_tr_b16 v[128:129], v168 offset:12288
	ds_read_b64_tr_b16 v[130:131], v168 offset:14336
	s_waitcnt lgkmcnt(10)
	v_mfma_f32_32x32x16_bf16 v[192:207], v[244:247], v[100:103], v[192:207]
	ds_read_b64_tr_b16 v[132:133], v168 offset:512
	ds_read_b64_tr_b16 v[134:135], v168 offset:2560
	s_waitcnt lgkmcnt(11)
	v_mfma_f32_32x32x16_bf16 v[112:127], v[248:251], v[96:99], v[112:127]
	ds_read_b64_tr_b16 v[140:141], v168 offset:4608
	ds_read_b64_tr_b16 v[142:143], v168 offset:6656
	s_waitcnt lgkmcnt(12)
	v_mfma_f32_32x32x16_bf16 v[192:207], v[188:191], v[96:99], v[192:207]
	ds_read_b64_tr_b16 v[152:153], v168 offset:8704
	ds_read_b64_tr_b16 v[154:155], v168 offset:10752
	s_waitcnt lgkmcnt(12)
	v_mfma_f32_32x32x16_bf16 v[0:15], v[208:211], v[84:87], v[0:15]
	ds_read_b64_tr_b16 v[160:161], v168 offset:12800
	ds_read_b64_tr_b16 v[162:163], v168 offset:14848
	s_waitcnt lgkmcnt(12)
	v_mfma_f32_32x32x16_bf16 v[0:15], v[212:215], v[88:91], v[0:15]
	ds_read_b64_tr_b16 v[84:85], v168 offset:1024
	ds_read_b64_tr_b16 v[86:87], v168 offset:3072
	s_waitcnt lgkmcnt(12)
	v_mfma_f32_32x32x16_bf16 v[0:15], v[216:219], v[92:95], v[0:15]
	ds_read_b64_tr_b16 v[88:89], v168 offset:5120
	ds_read_b64_tr_b16 v[90:91], v168 offset:7168
	s_waitcnt lgkmcnt(12)
	v_mfma_f32_32x32x16_bf16 v[0:15], v[220:223], v[128:131], v[0:15]
	ds_read_b64_tr_b16 v[92:93], v168 offset:9216
	ds_read_b64_tr_b16 v[94:95], v168 offset:11264
	s_waitcnt lgkmcnt(12)
	v_mfma_f32_32x32x16_bf16 v[16:31], v[208:211], v[132:135], v[16:31]
	ds_read_b64_tr_b16 v[128:129], v168 offset:13312
	ds_read_b64_tr_b16 v[130:131], v168 offset:15360
	s_mov_b32 m0, s31
	s_add_u32 s7, s31, 0x2000
	global_load_lds_dwordx4 v169, s[24:25]
	s_waitcnt lgkmcnt(12)
	v_mfma_f32_32x32x16_bf16 v[16:31], v[212:215], v[140:143], v[16:31]
	ds_read_b64_tr_b16 v[132:133], v168 offset:1536
	ds_read_b64_tr_b16 v[134:135], v168 offset:3584
	s_waitcnt lgkmcnt(12)
	v_mfma_f32_32x32x16_bf16 v[16:31], v[216:219], v[152:155], v[16:31]
	ds_read_b64_tr_b16 v[140:141], v168 offset:5632
	ds_read_b64_tr_b16 v[142:143], v168 offset:7680
	s_waitcnt lgkmcnt(12)
	v_mfma_f32_32x32x16_bf16 v[16:31], v[220:223], v[160:163], v[16:31]
	ds_read_b64_tr_b16 v[152:153], v168 offset:9728
	ds_read_b64_tr_b16 v[154:155], v168 offset:11776
	s_mov_b32 m0, s7
	s_xor_b32 s31, s31, 0x4000
	global_load_lds_dwordx4 v170, s[24:25]
	s_add_u32 s24, s24, 0x50000
	s_addc_u32 s25, s25, 0
	s_waitcnt lgkmcnt(12)
	v_mfma_f32_32x32x16_bf16 v[32:47], v[208:211], v[84:87], v[32:47]
	ds_read_b64_tr_b16 v[160:161], v168 offset:13824
	ds_read_b64_tr_b16 v[162:163], v168 offset:15872
	v_xor_b32_e32 v168, 0x4000, v168
	s_waitcnt lgkmcnt(12)
	v_mfma_f32_32x32x16_bf16 v[32:47], v[212:215], v[88:91], v[32:47]
	s_waitcnt lgkmcnt(10)
	v_mfma_f32_32x32x16_bf16 v[32:47], v[216:219], v[92:95], v[32:47]
	s_mov_b32 m0, s33
	s_add_u32 s7, s33, 0x2000
	global_load_lds_dwordx4 v171, s[26:27]
	s_waitcnt lgkmcnt(8)
	v_mfma_f32_32x32x16_bf16 v[32:47], v[220:223], v[128:131], v[32:47]
	s_waitcnt lgkmcnt(6)
	v_mfma_f32_32x32x16_bf16 v[48:63], v[208:211], v[132:135], v[48:63]
	s_waitcnt lgkmcnt(4)
	v_mfma_f32_32x32x16_bf16 v[48:63], v[212:215], v[140:143], v[48:63]
	s_mov_b32 m0, s7
	s_xor_b32 s33, s33, 0x4000
	global_load_lds_dwordx4 v172, s[26:27]
	s_add_u32 s26, s26, 0x50000
	s_addc_u32 s27, s27, 0
	s_waitcnt lgkmcnt(2)
	v_mfma_f32_32x32x16_bf16 v[48:63], v[216:219], v[152:155], v[48:63]
	s_waitcnt lgkmcnt(0)
	v_mfma_f32_32x32x16_bf16 v[48:63], v[220:223], v[160:163], v[48:63]
	s_add_i32 s34, s34, 1
	s_add_i32 s23, s23, 64
	s_addk_i32 s35, 0x100
	s_barrier
	s_cmp_lt_u32 s34, s20
	s_cbranch_scc1 .Lat_g0_loop
	s_setprio 1
	s_cmp_gt_i32 s23, s29
	s_cselect_b32 s99, 1, 0
	s_cmp_lt_i32 s23, s30
	s_cselect_b32 s6, 1, 0
	s_and_b32 s99, s99, s6
	s_cbranch_scc0 .Lat_far_g0p
	v_add_u32_e32 v186, s35, v174
	ds_read2_b32 v[224:225], v186 offset0:0 offset1:1
	ds_read2_b32 v[226:227], v186 offset0:2 offset1:3
	ds_read2_b32 v[228:229], v186 offset0:8 offset1:9
	ds_read2_b32 v[230:231], v186 offset0:10 offset1:11
	ds_read2_b32 v[232:233], v186 offset0:16 offset1:17
	ds_read2_b32 v[234:235], v186 offset0:18 offset1:19
	ds_read2_b32 v[236:237], v186 offset0:24 offset1:25
	ds_read2_b32 v[238:239], v186 offset0:26 offset1:27
	s_waitcnt lgkmcnt(4)
	ds_read2_b32 v[240:241], v186 offset0:32 offset1:33
	ds_read2_b32 v[242:243], v186 offset0:34 offset1:35
	ds_read2_b32 v[244:245], v186 offset0:40 offset1:41
	ds_read2_b32 v[246:247], v186 offset0:42 offset1:43
	ds_read2_b32 v[248:249], v186 offset0:48 offset1:49
	ds_read2_b32 v[250:251], v186 offset0:50 offset1:51
	ds_read2_b32 v[188:189], v186 offset0:56 offset1:57
	ds_read2_b32 v[190:191], v186 offset0:58 offset1:59
	s_waitcnt lgkmcnt(8)
	v_add_f32_e32 v112, v112, v224
	v_add_f32_e32 v113, v113, v225
	v_add_f32_e32 v114, v114, v226
	v_add_f32_e32 v115, v115, v227
	v_add_f32_e32 v116, v116, v228
	v_add_f32_e32 v117, v117, v229
	v_add_f32_e32 v118, v118, v230
	v_add_f32_e32 v119, v119, v231
	v_add_f32_e32 v120, v120, v232
	v_add_f32_e32 v121, v121, v233
	v_add_f32_e32 v122, v122, v234
	v_add_f32_e32 v123, v123, v235
	v_add_f32_e32 v124, v124, v236
	v_add_f32_e32 v125, v125, v237
	v_add_f32_e32 v126, v126, v238
	v_add_f32_e32 v127, v127, v239
	s_waitcnt lgkmcnt(0)
	v_add_f32_e32 v192, v192, v240
	v_add_f32_e32 v193, v193, v241
	v_add_f32_e32 v194, v194, v242
	v_add_f32_e32 v195, v195, v243
	v_add_f32_e32 v196, v196, v244
	v_add_f32_e32 v197, v197, v245
	v_add_f32_e32 v198, v198, v246
	v_add_f32_e32 v199, v199, v247
	v_add_f32_e32 v200, v200, v248
	v_add_f32_e32 v201, v201, v249
	v_add_f32_e32 v202, v202, v250
	v_add_f32_e32 v203, v203, v251
	v_add_f32_e32 v204, v204, v188
	v_add_f32_e32 v205, v205, v189
	v_add_f32_e32 v206, v206, v190
	v_add_f32_e32 v207, v207, v191
; #define SBAR() __builtin_amdgcn_sched_barrier(0)
; #define PVLOAD(D0, X) do { X[0] = tr_read<v_rd_off(D0, 0, 0)>(vb); X[1] = tr_read<v_rd_off(D0, 0, 1)>(vb); X[2] = tr_read<v_rd_off(D0, 1, 0)>(vb); X[3] = tr_read<v_rd_off(D0, 1, 1)>(vb); \
;     X[4] = tr_read<v_rd_off(D0, 2, 0)>(vb); X[5] = tr_read<v_rd_off(D0, 2, 1)>(vb); X[6] = tr_read<v_rd_off(D0, 3, 0)>(vb); X[7] = tr_read<v_rd_off(D0, 3, 1)>(vb); } while (0)
; #define PVMMA(OD, X) do { OD = __builtin_amdgcn_mfma_f32_32x32x16_bf16(pa0, PVPK(X[0], X[1]), OD, 0, 0, 0); OD = __builtin_amdgcn_mfma_f32_32x32x16_bf16(pa1, PVPK(X[2], X[3]), OD, 0, 0, 0); \
;     OD = __builtin_amdgcn_mfma_f32_32x32x16_bf16(pa2, PVPK(X[4], X[5]), OD, 0, 0, 0); OD = __builtin_amdgcn_mfma_f32_32x32x16_bf16(pa3, PVPK(X[6], X[7]), OD, 0, 0, 0); } while (0)
; #define PVWAIT() do { asm volatile("s_waitcnt lgkmcnt(0)" ::: "memory"); SBAR(); } while (0)
; #define PVEXP(P, B, N) do { _Pragma("unroll") for (int r = (B); r < (B) + (N); ++r) P[r] = __builtin_amdgcn_exp2f(P[r]); } while (0)
; __device__ __forceinline__ void expHalf(f32x16& p0) {
; #pragma unroll
;     for (int r = 0; r < 16; ++r) p0[r] = __builtin_amdgcn_exp2f(p0[r]);
; }
; __device__ __forceinline__ void finishSM(f32x16& p0, f32x16& p1, float& l_reg, bf16x8& pa0, bf16x8& pa1, bf16x8& pa2, bf16x8& pa3) {
;     float ps = 0;
; #pragma unroll
;     for (int r = 0; r < 16; ++r) ps += p0[r];
; #pragma unroll
;     for (int r = 0; r < 16; ++r) ps += p1[r];
;     l_reg += ps;
;     ...
;     PK4(p0, 0, pa0); PK4(p0, 8, pa1); PK4(p1, 0, pa2); PK4(p1, 8, pa3);
;     ...
; }
; template <int NB> __device__ __forceinline__ void pv_blocks(f32x16* o, int vb, bf16x8 pa0, bf16x8 pa1, bf16x8 pa2, bf16x8 pa3, f32x16& pe0, f32x16& pe1) {
;     s16x4 x[8], y[8];
;     ...
;     PVLOAD(0, x); PVWAIT();
;     if (NB == 4) {
;         PVLOAD(1, y); SBAR(); PVMMA(o[0], x); PVEXP(pe0, 0, 8); SBAR(); PVWAIT();
;         PVLOAD(2, x); SBAR(); PVMMA(o[1], y); PVEXP(pe0, 8, 8); SBAR(); PVWAIT();
;         PVLOAD(3, y); SBAR(); PVMMA(o[2], x); PVEXP(pe1, 0, 8); SBAR(); PVWAIT();
;         PVMMA(o[3], y); PVEXP(pe1, 8, 8);
;     } else {
;         PVLOAD(1, y); SBAR(); PVMMA(o[0], x); PVEXP(pe0, 0, 16); SBAR(); PVWAIT();
;         PVMMA(o[1], y); PVEXP(pe1, 0, 16);
;     }
;     ...
; }
.Lat_far_g0p:
	v_exp_f32_e32 v112, v112
	v_exp_f32_e32 v113, v113
	v_exp_f32_e32 v114, v114
	v_exp_f32_e32 v115, v115
	v_exp_f32_e32 v116, v116
	v_exp_f32_e32 v117, v117
	v_exp_f32_e32 v118, v118
	v_exp_f32_e32 v119, v119
	v_exp_f32_e32 v120, v120
	v_exp_f32_e32 v121, v121
	v_exp_f32_e32 v122, v122
	v_exp_f32_e32 v123, v123
	v_exp_f32_e32 v124, v124
	v_exp_f32_e32 v125, v125
	v_exp_f32_e32 v126, v126
	v_exp_f32_e32 v127, v127
	v_exp_f32_e32 v192, v192
	v_add_f32_e32 v64, v64, v112
	v_exp_f32_e32 v193, v193
	v_add_f32_e32 v65, v65, v113
	v_exp_f32_e32 v194, v194
	v_add_f32_e32 v66, v66, v114
	v_exp_f32_e32 v195, v195
	v_add_f32_e32 v67, v67, v115
	v_exp_f32_e32 v196, v196
	v_add_f32_e32 v64, v64, v116
	v_exp_f32_e32 v197, v197
	v_add_f32_e32 v65, v65, v117
	v_exp_f32_e32 v198, v198
	v_add_f32_e32 v66, v66, v118
	v_exp_f32_e32 v199, v199
	v_add_f32_e32 v67, v67, v119
	v_exp_f32_e32 v200, v200
	v_add_f32_e32 v64, v64, v120
	v_exp_f32_e32 v201, v201
	v_add_f32_e32 v65, v65, v121
	v_exp_f32_e32 v202, v202
	v_add_f32_e32 v66, v66, v122
	v_exp_f32_e32 v203, v203
	v_add_f32_e32 v67, v67, v123
	v_exp_f32_e32 v204, v204
	v_add_f32_e32 v64, v64, v124
	v_exp_f32_e32 v205, v205
	v_add_f32_e32 v65, v65, v125
	v_exp_f32_e32 v206, v206
	v_add_f32_e32 v66, v66, v126
	v_exp_f32_e32 v207, v207
	v_add_f32_e32 v67, v67, v127
	v_cvt_pk_bf16_f32 v208, v112, v113
	v_cvt_pk_bf16_f32 v209, v114, v115
	v_cvt_pk_bf16_f32 v210, v116, v117
	v_cvt_pk_bf16_f32 v211, v118, v119
	v_cvt_pk_bf16_f32 v212, v120, v121
	v_cvt_pk_bf16_f32 v213, v122, v123
	v_cvt_pk_bf16_f32 v214, v124, v125
	v_cvt_pk_bf16_f32 v215, v126, v127
	v_add_f32_e32 v64, v64, v192
	v_add_f32_e32 v65, v65, v193
	v_add_f32_e32 v66, v66, v194
	v_add_f32_e32 v67, v67, v195
	v_add_f32_e32 v64, v64, v196
	v_add_f32_e32 v65, v65, v197
	v_add_f32_e32 v66, v66, v198
	v_add_f32_e32 v67, v67, v199
	v_add_f32_e32 v64, v64, v200
	v_add_f32_e32 v65, v65, v201
	v_add_f32_e32 v66, v66, v202
	v_add_f32_e32 v67, v67, v203
	v_add_f32_e32 v64, v64, v204
	v_add_f32_e32 v65, v65, v205
	v_add_f32_e32 v66, v66, v206
	v_add_f32_e32 v67, v67, v207
	v_cvt_pk_bf16_f32 v216, v192, v193
	v_cvt_pk_bf16_f32 v217, v194, v195
	v_cvt_pk_bf16_f32 v218, v196, v197
	v_cvt_pk_bf16_f32 v219, v198, v199
	v_cvt_pk_bf16_f32 v220, v200, v201
	v_cvt_pk_bf16_f32 v221, v202, v203
	v_cvt_pk_bf16_f32 v222, v204, v205
	v_cvt_pk_bf16_f32 v223, v206, v207
	s_nop 1
	s_waitcnt vmcnt(0)
	s_barrier
	s_setprio 0
	ds_read_b64_tr_b16 v[84:85], v168 offset:0
	ds_read_b64_tr_b16 v[86:87], v168 offset:2048
	ds_read_b64_tr_b16 v[88:89], v168 offset:4096
	ds_read_b64_tr_b16 v[90:91], v168 offset:6144
	ds_read_b64_tr_b16 v[92:93], v168 offset:8192
	ds_read_b64_tr_b16 v[94:95], v168 offset:10240
	ds_read_b64_tr_b16 v[128:129], v168 offset:12288
	ds_read_b64_tr_b16 v[130:131], v168 offset:14336
	ds_read_b64_tr_b16 v[132:133], v168 offset:512
	ds_read_b64_tr_b16 v[134:135], v168 offset:2560
	ds_read_b64_tr_b16 v[140:141], v168 offset:4608
	ds_read_b64_tr_b16 v[142:143], v168 offset:6656
	ds_read_b64_tr_b16 v[152:153], v168 offset:8704
	ds_read_b64_tr_b16 v[154:155], v168 offset:10752
	s_waitcnt lgkmcnt(12)
	v_mfma_f32_32x32x16_bf16 v[0:15], v[208:211], v[84:87], v[0:15]
	ds_read_b64_tr_b16 v[160:161], v168 offset:12800
	ds_read_b64_tr_b16 v[162:163], v168 offset:14848
	s_waitcnt lgkmcnt(12)
	v_mfma_f32_32x32x16_bf16 v[0:15], v[212:215], v[88:91], v[0:15]
	ds_read_b64_tr_b16 v[84:85], v168 offset:1024
	ds_read_b64_tr_b16 v[86:87], v168 offset:3072
	s_waitcnt lgkmcnt(12)
	v_mfma_f32_32x32x16_bf16 v[0:15], v[216:219], v[92:95], v[0:15]
	ds_read_b64_tr_b16 v[88:89], v168 offset:5120
	ds_read_b64_tr_b16 v[90:91], v168 offset:7168
	s_waitcnt lgkmcnt(12)
	v_mfma_f32_32x32x16_bf16 v[0:15], v[220:223], v[128:131], v[0:15]
	ds_read_b64_tr_b16 v[92:93], v168 offset:9216
	ds_read_b64_tr_b16 v[94:95], v168 offset:11264
	s_waitcnt lgkmcnt(12)
	v_mfma_f32_32x32x16_bf16 v[16:31], v[208:211], v[132:135], v[16:31]
	ds_read_b64_tr_b16 v[128:129], v168 offset:13312
	ds_read_b64_tr_b16 v[130:131], v168 offset:15360
	s_waitcnt lgkmcnt(12)
	v_mfma_f32_32x32x16_bf16 v[16:31], v[212:215], v[140:143], v[16:31]
	ds_read_b64_tr_b16 v[132:133], v168 offset:1536
	ds_read_b64_tr_b16 v[134:135], v168 offset:3584
	s_waitcnt lgkmcnt(12)
	v_mfma_f32_32x32x16_bf16 v[16:31], v[216:219], v[152:155], v[16:31]
	ds_read_b64_tr_b16 v[140:141], v168 offset:5632
	ds_read_b64_tr_b16 v[142:143], v168 offset:7680
	s_waitcnt lgkmcnt(12)
	v_mfma_f32_32x32x16_bf16 v[16:31], v[220:223], v[160:163], v[16:31]
	ds_read_b64_tr_b16 v[152:153], v168 offset:9728
	ds_read_b64_tr_b16 v[154:155], v168 offset:11776
	s_waitcnt lgkmcnt(12)
	v_mfma_f32_32x32x16_bf16 v[32:47], v[208:211], v[84:87], v[32:47]
	ds_read_b64_tr_b16 v[160:161], v168 offset:13824
	ds_read_b64_tr_b16 v[162:163], v168 offset:15872
	v_xor_b32_e32 v168, 0x4000, v168
	s_waitcnt lgkmcnt(12)
	v_mfma_f32_32x32x16_bf16 v[32:47], v[212:215], v[88:91], v[32:47]
	s_waitcnt lgkmcnt(10)
	v_mfma_f32_32x32x16_bf16 v[32:47], v[216:219], v[92:95], v[32:47]
	s_waitcnt lgkmcnt(8)
	v_mfma_f32_32x32x16_bf16 v[32:47], v[220:223], v[128:131], v[32:47]
	s_waitcnt lgkmcnt(6)
	v_mfma_f32_32x32x16_bf16 v[48:63], v[208:211], v[132:135], v[48:63]
	s_waitcnt lgkmcnt(4)
	v_mfma_f32_32x32x16_bf16 v[48:63], v[212:215], v[140:143], v[48:63]
	s_waitcnt lgkmcnt(2)
	v_mfma_f32_32x32x16_bf16 v[48:63], v[216:219], v[152:155], v[48:63]
	s_waitcnt lgkmcnt(0)
	v_mfma_f32_32x32x16_bf16 v[48:63], v[220:223], v[160:163], v[48:63]
	s_barrier
	s_barrier
	s_branch .Lat_done

; #define SBAR() __builtin_amdgcn_sched_barrier(0)
; #define KFRAG(d0, row) (*reinterpret_cast<const bf16x8*>(Ks + KSWZ((row), (half * 64 + (d0) * 16 + hi * 8) * 2)))
; __device__ __forceinline__ void expHalf(f32x16& p0) {
; #pragma unroll
;     for (int r = 0; r < 16; ++r) p0[r] = __builtin_amdgcn_exp2f(p0[r]);
; }
; __device__ __forceinline__ void finishSM(f32x16& p0, f32x16& p1, float& l_reg, bf16x8& pa0, bf16x8& pa1, bf16x8& pa2, bf16x8& pa3) {
;     float ps = 0;
; #pragma unroll
;     for (int r = 0; r < 16; ++r) ps += p0[r];
; #pragma unroll
;     for (int r = 0; r < 16; ++r) ps += p1[r];
;     l_reg += ps;
;     ...
;     PK4(p0, 0, pa0); PK4(p0, 8, pa1); PK4(p1, 0, pa2); PK4(p1, 8, pa3);
;     ...
; }
; __device__ __forceinline__ void qkt(f32x16& p0, f32x16& p1, const char* Ks, const bf16x8* qr, float c0, int r32, int hi, int half) {
;     ...
;     bf16x8 a0 = KFRAG(0, r32), a1 = KFRAG(0, 32 + r32), b0 = KFRAG(1, r32), b1 = KFRAG(1, 32 + r32);
;     SBAR();
; #pragma unroll
;     for (int r = 0; r < 16; ++r) { p0[r] = c0; p1[r] = c0; }
;     SBAR();
;     p0 = __builtin_amdgcn_mfma_f32_32x32x16_bf16(a0, qr[0], p0, 0, 0, 0); p1 = __builtin_amdgcn_mfma_f32_32x32x16_bf16(a1, qr[0], p1, 0, 0, 0);
;     a0 = KFRAG(2, r32); a1 = KFRAG(2, 32 + r32);
;     SBAR();
;     p0 = __builtin_amdgcn_mfma_f32_32x32x16_bf16(b0, qr[1], p0, 0, 0, 0); p1 = __builtin_amdgcn_mfma_f32_32x32x16_bf16(b1, qr[1], p1, 0, 0, 0);
;     b0 = KFRAG(3, r32); b1 = KFRAG(3, 32 + r32);
;     SBAR();
;     p0 = __builtin_amdgcn_mfma_f32_32x32x16_bf16(a0, qr[2], p0, 0, 0, 0); p1 = __builtin_amdgcn_mfma_f32_32x32x16_bf16(a1, qr[2], p1, 0, 0, 0);
;     p0 = __builtin_amdgcn_mfma_f32_32x32x16_bf16(b0, qr[3], p0, 0, 0, 0); p1 = __builtin_amdgcn_mfma_f32_32x32x16_bf16(b1, qr[3], p1, 0, 0, 0);
;     ...
; }
; template <int MODE>
; __device__ __forceinline__ void attn_unit(const UnitArgs& A, char* lds, const int wave_) {
;     ...
;     auto zone_of = [&](int t) -> int { const int k0 = 64 * t, qw0 = A.q0 + 32 * qb; return (k0 + 63 - qw0 <= -128) ? 0 : ((k0 - qw0 - 31 >= 128) ? 2 : 1); };
.Lat_far_g1l:
	s_mov_b32 m0, s31
	s_add_u32 s7, s31, 0x2000
	global_load_lds_dwordx4 v169, s[24:25]
	v_exp_f32_e32 v112, v112
	v_exp_f32_e32 v113, v113
	v_exp_f32_e32 v114, v114
	v_exp_f32_e32 v115, v115
	v_exp_f32_e32 v116, v116
	v_exp_f32_e32 v117, v117
	v_exp_f32_e32 v118, v118
	v_exp_f32_e32 v119, v119
	s_mov_b32 m0, s7
	s_xor_b32 s31, s31, 0x4000
	global_load_lds_dwordx4 v170, s[24:25]
	s_add_u32 s24, s24, 0x50000
	s_addc_u32 s25, s25, 0
	v_exp_f32_e32 v120, v120
	v_exp_f32_e32 v121, v121
	v_exp_f32_e32 v122, v122
	v_exp_f32_e32 v123, v123
	v_exp_f32_e32 v124, v124
	v_exp_f32_e32 v125, v125
	v_exp_f32_e32 v126, v126
	v_exp_f32_e32 v127, v127
	s_mov_b32 m0, s33
	s_add_u32 s7, s33, 0x2000
	global_load_lds_dwordx4 v171, s[26:27]
	v_exp_f32_e32 v192, v192
	v_add_f32_e32 v64, v64, v112
	v_exp_f32_e32 v193, v193
	v_add_f32_e32 v65, v65, v113
	v_exp_f32_e32 v194, v194
	v_add_f32_e32 v66, v66, v114
	v_exp_f32_e32 v195, v195
	v_add_f32_e32 v67, v67, v115
	v_exp_f32_e32 v196, v196
	v_add_f32_e32 v64, v64, v116
	v_exp_f32_e32 v197, v197
	v_add_f32_e32 v65, v65, v117
	s_mov_b32 m0, s7
	s_xor_b32 s33, s33, 0x4000
	global_load_lds_dwordx4 v172, s[26:27]
	s_add_u32 s26, s26, 0x50000
	s_addc_u32 s27, s27, 0
	v_exp_f32_e32 v198, v198
	v_add_f32_e32 v66, v66, v118
	v_exp_f32_e32 v199, v199
	v_add_f32_e32 v67, v67, v119
	v_exp_f32_e32 v200, v200
	v_add_f32_e32 v64, v64, v120
	v_exp_f32_e32 v201, v201
	v_add_f32_e32 v65, v65, v121
	v_exp_f32_e32 v202, v202
	v_add_f32_e32 v66, v66, v122
	v_exp_f32_e32 v203, v203
	v_add_f32_e32 v67, v67, v123
	v_exp_f32_e32 v204, v204
	v_add_f32_e32 v64, v64, v124
	v_exp_f32_e32 v205, v205
	v_add_f32_e32 v65, v65, v125
	v_exp_f32_e32 v206, v206
	v_add_f32_e32 v66, v66, v126
	v_exp_f32_e32 v207, v207
	v_add_f32_e32 v67, v67, v127
	v_cvt_pk_bf16_f32 v208, v112, v113
	v_cvt_pk_bf16_f32 v209, v114, v115
	v_cvt_pk_bf16_f32 v210, v116, v117
	v_cvt_pk_bf16_f32 v211, v118, v119
	v_cvt_pk_bf16_f32 v212, v120, v121
	v_cvt_pk_bf16_f32 v213, v122, v123
	v_cvt_pk_bf16_f32 v214, v124, v125
	v_cvt_pk_bf16_f32 v215, v126, v127
	v_add_f32_e32 v64, v64, v192
	v_add_f32_e32 v65, v65, v193
	v_add_f32_e32 v66, v66, v194
	v_add_f32_e32 v67, v67, v195
	v_add_f32_e32 v64, v64, v196
	v_add_f32_e32 v65, v65, v197
	v_add_f32_e32 v66, v66, v198
	v_add_f32_e32 v67, v67, v199
	v_add_f32_e32 v64, v64, v200
	v_add_f32_e32 v65, v65, v201
	v_add_f32_e32 v66, v66, v202
	v_add_f32_e32 v67, v67, v203
	v_add_f32_e32 v64, v64, v204
	v_add_f32_e32 v65, v65, v205
	v_add_f32_e32 v66, v66, v206
	v_add_f32_e32 v67, v67, v207
	v_cvt_pk_bf16_f32 v216, v192, v193
	v_cvt_pk_bf16_f32 v217, v194, v195
	v_cvt_pk_bf16_f32 v218, v196, v197
	v_cvt_pk_bf16_f32 v219, v198, v199
	v_cvt_pk_bf16_f32 v220, v200, v201
	v_cvt_pk_bf16_f32 v221, v202, v203
	v_cvt_pk_bf16_f32 v222, v204, v205
	v_cvt_pk_bf16_f32 v223, v206, v207
	s_add_i32 s99, s23, 64
	s_cmp_ge_i32 s99, s30
	s_cselect_b32 s6, s22, s98
	s_cmp_le_i32 s99, s29
	s_cselect_b32 s6, s21, s6
	s_nop 0
	s_cmp_lg_u32 s6, s9
	s_cbranch_scc0 .Lat_c0same_g1l
	s_mov_b32 s9, s6
	v_mov_b32_e32 v68, s9
	v_mov_b32_e32 v69, s9
	v_mov_b32_e32 v70, s9
	v_mov_b32_e32 v71, s9
	v_mov_b32_e32 v72, s9
	v_mov_b32_e32 v73, s9
	v_mov_b32_e32 v74, s9
	v_mov_b32_e32 v75, s9
	v_mov_b32_e32 v76, s9
	v_mov_b32_e32 v77, s9
	v_mov_b32_e32 v78, s9
	v_mov_b32_e32 v79, s9
	v_mov_b32_e32 v80, s9
	v_mov_b32_e32 v81, s9
	v_mov_b32_e32 v82, s9
	v_mov_b32_e32 v83, s9
.Lat_c0same_g1l:
	ds_read_b128 v[224:227], v164
	ds_read_b128 v[228:231], v164 offset:8192
	ds_read_b128 v[232:235], v165
	ds_read_b128 v[236:239], v165 offset:8192
	ds_read_b128 v[240:243], v166
	ds_read_b128 v[244:247], v166 offset:8192
	ds_read_b128 v[248:251], v167
	ds_read_b128 v[188:191], v167 offset:8192
	v_xor_b32_e32 v164, 0x4000, v164
	v_xor_b32_e32 v165, 0x4000, v165
	v_xor_b32_e32 v166, 0x4000, v166
	v_xor_b32_e32 v167, 0x4000, v167
	s_barrier
	s_setprio 0
	s_waitcnt lgkmcnt(7)
	v_mfma_f32_32x32x16_bf16 v[112:127], v[224:227], v[108:111], v[68:83]
	s_waitcnt lgkmcnt(6)
	v_mfma_f32_32x32x16_bf16 v[192:207], v[228:231], v[108:111], v[68:83]
	ds_read_b64_tr_b16 v[84:85], v168 offset:0
	ds_read_b64_tr_b16 v[86:87], v168 offset:2048
	s_waitcnt lgkmcnt(7)
	v_mfma_f32_32x32x16_bf16 v[112:127], v[232:235], v[104:107], v[112:127]
	ds_read_b64_tr_b16 v[88:89], v168 offset:4096
	ds_read_b64_tr_b16 v[90:91], v168 offset:6144
	s_waitcnt lgkmcnt(8)
	v_mfma_f32_32x32x16_bf16 v[192:207], v[236:239], v[104:107], v[192:207]
	ds_read_b64_tr_b16 v[92:93], v168 offset:8192
	ds_read_b64_tr_b16 v[94:95], v168 offset:10240
	s_waitcnt lgkmcnt(9)
	v_mfma_f32_32x32x16_bf16 v[112:127], v[240:243], v[100:103], v[112:127]
	ds_read_b64_tr_b16 v[128:129], v168 offset:12288
	ds_read_b64_tr_b16 v[130:131], v168 offset:14336
	s_waitcnt lgkmcnt(10)
	v_mfma_f32_32x32x16_bf16 v[192:207], v[244:247], v[100:103], v[192:207]
	ds_read_b64_tr_b16 v[132:133], v168 offset:512
	ds_read_b64_tr_b16 v[134:135], v168 offset:2560
	s_waitcnt lgkmcnt(11)
	v_mfma_f32_32x32x16_bf16 v[112:127], v[248:251], v[96:99], v[112:127]
	ds_read_b64_tr_b16 v[140:141], v168 offset:4608
	ds_read_b64_tr_b16 v[142:143], v168 offset:6656
	s_waitcnt lgkmcnt(12)
	v_mfma_f32_32x32x16_bf16 v[192:207], v[188:191], v[96:99], v[192:207]
	ds_read_b64_tr_b16 v[152:153], v168 offset:8704
	ds_read_b64_tr_b16 v[154:155], v168 offset:10752
	s_waitcnt lgkmcnt(12)
	v_mfma_f32_32x32x16_bf16 v[0:15], v[208:211], v[84:87], v[0:15]
	ds_read_b64_tr_b16 v[160:161], v168 offset:12800
	ds_read_b64_tr_b16 v[162:163], v168 offset:14848
	s_waitcnt lgkmcnt(12)
	v_mfma_f32_32x32x16_bf16 v[0:15], v[212:215], v[88:91], v[0:15]
	ds_read_b64_tr_b16 v[84:85], v168 offset:1024
	ds_read_b64_tr_b16 v[86:87], v168 offset:3072
	s_waitcnt lgkmcnt(12)
; #define SBAR() __builtin_amdgcn_sched_barrier(0)
; #define PVLOAD(D0, X) do { X[0] = tr_read<v_rd_off(D0, 0, 0)>(vb); X[1] = tr_read<v_rd_off(D0, 0, 1)>(vb); X[2] = tr_read<v_rd_off(D0, 1, 0)>(vb); X[3] = tr_read<v_rd_off(D0, 1, 1)>(vb); \
;     X[4] = tr_read<v_rd_off(D0, 2, 0)>(vb); X[5] = tr_read<v_rd_off(D0, 2, 1)>(vb); X[6] = tr_read<v_rd_off(D0, 3, 0)>(vb); X[7] = tr_read<v_rd_off(D0, 3, 1)>(vb); } while (0)
; #define PVMMA(OD, X) do { OD = __builtin_amdgcn_mfma_f32_32x32x16_bf16(pa0, PVPK(X[0], X[1]), OD, 0, 0, 0); OD = __builtin_amdgcn_mfma_f32_32x32x16_bf16(pa1, PVPK(X[2], X[3]), OD, 0, 0, 0); \
;     OD = __builtin_amdgcn_mfma_f32_32x32x16_bf16(pa2, PVPK(X[4], X[5]), OD, 0, 0, 0); OD = __builtin_amdgcn_mfma_f32_32x32x16_bf16(pa3, PVPK(X[6], X[7]), OD, 0, 0, 0); } while (0)
; #define PVWAIT() do { asm volatile("s_waitcnt lgkmcnt(0)" ::: "memory"); SBAR(); } while (0)
; #define PVEXP(P, B, N) do { _Pragma("unroll") for (int r = (B); r < (B) + (N); ++r) P[r] = __builtin_amdgcn_exp2f(P[r]); } while (0)
; template <int NB> __device__ __forceinline__ void pv_blocks(f32x16* o, int vb, bf16x8 pa0, bf16x8 pa1, bf16x8 pa2, bf16x8 pa3, f32x16& pe0, f32x16& pe1) {
;     s16x4 x[8], y[8];
;     ...
;     PVLOAD(0, x); PVWAIT();
;     if (NB == 4) {
;         PVLOAD(1, y); SBAR(); PVMMA(o[0], x); PVEXP(pe0, 0, 8); SBAR(); PVWAIT();
;         PVLOAD(2, x); SBAR(); PVMMA(o[1], y); PVEXP(pe0, 8, 8); SBAR(); PVWAIT();
;         PVLOAD(3, y); SBAR(); PVMMA(o[2], x); PVEXP(pe1, 0, 8); SBAR(); PVWAIT();
;         PVMMA(o[3], y); PVEXP(pe1, 8, 8);
;     } else {
;         PVLOAD(1, y); SBAR(); PVMMA(o[0], x); PVEXP(pe0, 0, 16); SBAR(); PVWAIT();
;         PVMMA(o[1], y); PVEXP(pe1, 0, 16);
;     }
;     ...
; }
; template <int MODE>
; __device__ __forceinline__ void attn_unit(const UnitArgs& A, char* lds, const int wave_) {
;     ...
;     auto post = [&](f32x16& p0, f32x16& p1, int t) {
;         SBAR();
;         if (MODE == 0) {
;             if (zone_of(t) == 1) { const int k0 = 64 * t, qw0 = A.q0 + 32 * qb;
;                 const float* b = lutA + A.h * LUTA_STRIDE + (k0 - qw0 - r32 + 4 * hi + 320);
; #pragma unroll
;                 for (int r = 0; r < 16; ++r) { const int c = (r & 3) + 8 * (r >> 2); p0[r] += b[c]; p1[r] += b[32 + c]; } }
	v_mfma_f32_32x32x16_bf16 v[0:15], v[216:219], v[92:95], v[0:15]
	ds_read_b64_tr_b16 v[88:89], v168 offset:5120
	ds_read_b64_tr_b16 v[90:91], v168 offset:7168
	s_waitcnt lgkmcnt(12)
	v_mfma_f32_32x32x16_bf16 v[0:15], v[220:223], v[128:131], v[0:15]
	ds_read_b64_tr_b16 v[92:93], v168 offset:9216
	ds_read_b64_tr_b16 v[94:95], v168 offset:11264
	s_waitcnt lgkmcnt(12)
	v_mfma_f32_32x32x16_bf16 v[16:31], v[208:211], v[132:135], v[16:31]
	ds_read_b64_tr_b16 v[128:129], v168 offset:13312
	ds_read_b64_tr_b16 v[130:131], v168 offset:15360
	s_waitcnt lgkmcnt(12)
	v_mfma_f32_32x32x16_bf16 v[16:31], v[212:215], v[140:143], v[16:31]
	ds_read_b64_tr_b16 v[132:133], v168 offset:1536
	ds_read_b64_tr_b16 v[134:135], v168 offset:3584
	s_waitcnt lgkmcnt(12)
	v_mfma_f32_32x32x16_bf16 v[16:31], v[216:219], v[152:155], v[16:31]
	ds_read_b64_tr_b16 v[140:141], v168 offset:5632
	ds_read_b64_tr_b16 v[142:143], v168 offset:7680
	s_waitcnt lgkmcnt(12)
	v_mfma_f32_32x32x16_bf16 v[16:31], v[220:223], v[160:163], v[16:31]
	ds_read_b64_tr_b16 v[152:153], v168 offset:9728
	ds_read_b64_tr_b16 v[154:155], v168 offset:11776
	s_waitcnt lgkmcnt(12)
	v_mfma_f32_32x32x16_bf16 v[32:47], v[208:211], v[84:87], v[32:47]
	ds_read_b64_tr_b16 v[160:161], v168 offset:13824
	ds_read_b64_tr_b16 v[162:163], v168 offset:15872
	v_xor_b32_e32 v168, 0x4000, v168
	s_waitcnt lgkmcnt(12)
	v_mfma_f32_32x32x16_bf16 v[32:47], v[212:215], v[88:91], v[32:47]
	s_waitcnt lgkmcnt(10)
	v_mfma_f32_32x32x16_bf16 v[32:47], v[216:219], v[92:95], v[32:47]
	s_waitcnt lgkmcnt(8)
	v_mfma_f32_32x32x16_bf16 v[32:47], v[220:223], v[128:131], v[32:47]
	s_waitcnt lgkmcnt(6)
	v_mfma_f32_32x32x16_bf16 v[48:63], v[208:211], v[132:135], v[48:63]
	s_waitcnt lgkmcnt(4)
	v_mfma_f32_32x32x16_bf16 v[48:63], v[212:215], v[140:143], v[48:63]
	s_waitcnt lgkmcnt(2)
	v_mfma_f32_32x32x16_bf16 v[48:63], v[216:219], v[152:155], v[48:63]
	s_waitcnt lgkmcnt(0)
	v_mfma_f32_32x32x16_bf16 v[48:63], v[220:223], v[160:163], v[48:63]
	s_add_i32 s34, s34, 1
	s_add_i32 s23, s23, 64
	s_addk_i32 s35, 0x100
	s_waitcnt vmcnt(0)
	s_barrier
	s_cmp_lt_u32 s34, s20
	s_cbranch_scc1 .Lat_g1_loop
	s_setprio 1
	s_cmp_gt_i32 s23, s29
	s_cselect_b32 s99, 1, 0
	s_cmp_lt_i32 s23, s30
	s_cselect_b32 s6, 1, 0
	s_and_b32 s99, s99, s6
	s_cbranch_scc0 .Lat_far_g1p
	v_add_u32_e32 v186, s35, v174
	ds_read2_b32 v[224:225], v186 offset0:0 offset1:1
	ds_read2_b32 v[226:227], v186 offset0:2 offset1:3
	ds_read2_b32 v[228:229], v186 offset0:8 offset1:9
	ds_read2_b32 v[230:231], v186 offset0:10 offset1:11
	ds_read2_b32 v[232:233], v186 offset0:16 offset1:17
	ds_read2_b32 v[234:235], v186 offset0:18 offset1:19
	ds_read2_b32 v[236:237], v186 offset0:24 offset1:25
	ds_read2_b32 v[238:239], v186 offset0:26 offset1:27
	s_waitcnt lgkmcnt(4)
	ds_read2_b32 v[240:241], v186 offset0:32 offset1:33
	ds_read2_b32 v[242:243], v186 offset0:34 offset1:35
	ds_read2_b32 v[244:245], v186 offset0:40 offset1:41
	ds_read2_b32 v[246:247], v186 offset0:42 offset1:43
	ds_read2_b32 v[248:249], v186 offset0:48 offset1:49
	ds_read2_b32 v[250:251], v186 offset0:50 offset1:51
	ds_read2_b32 v[188:189], v186 offset0:56 offset1:57
	ds_read2_b32 v[190:191], v186 offset0:58 offset1:59
	s_waitcnt lgkmcnt(8)
	v_add_f32_e32 v112, v112, v224
	v_add_f32_e32 v113, v113, v225
	v_add_f32_e32 v114, v114, v226
	v_add_f32_e32 v115, v115, v227
	v_add_f32_e32 v116, v116, v228
	v_add_f32_e32 v117, v117, v229
	v_add_f32_e32 v118, v118, v230
	v_add_f32_e32 v119, v119, v231
	v_add_f32_e32 v120, v120, v232
	v_add_f32_e32 v121, v121, v233
	v_add_f32_e32 v122, v122, v234
	v_add_f32_e32 v123, v123, v235
	v_add_f32_e32 v124, v124, v236
	v_add_f32_e32 v125, v125, v237
	v_add_f32_e32 v126, v126, v238
	v_add_f32_e32 v127, v127, v239
	s_waitcnt lgkmcnt(0)
	v_add_f32_e32 v192, v192, v240
	v_add_f32_e32 v193, v193, v241
	v_add_f32_e32 v194, v194, v242
	v_add_f32_e32 v195, v195, v243
	v_add_f32_e32 v196, v196, v244
	v_add_f32_e32 v197, v197, v245
	v_add_f32_e32 v198, v198, v246
	v_add_f32_e32 v199, v199, v247
	v_add_f32_e32 v200, v200, v248
	v_add_f32_e32 v201, v201, v249
	v_add_f32_e32 v202, v202, v250
	v_add_f32_e32 v203, v203, v251
	v_add_f32_e32 v204, v204, v188
	v_add_f32_e32 v205, v205, v189
	v_add_f32_e32 v206, v206, v190
	v_add_f32_e32 v207, v207, v191
; #define SBAR() __builtin_amdgcn_sched_barrier(0)
; #define PVLOAD(D0, X) do { X[0] = tr_read<v_rd_off(D0, 0, 0)>(vb); X[1] = tr_read<v_rd_off(D0, 0, 1)>(vb); X[2] = tr_read<v_rd_off(D0, 1, 0)>(vb); X[3] = tr_read<v_rd_off(D0, 1, 1)>(vb); \
;     X[4] = tr_read<v_rd_off(D0, 2, 0)>(vb); X[5] = tr_read<v_rd_off(D0, 2, 1)>(vb); X[6] = tr_read<v_rd_off(D0, 3, 0)>(vb); X[7] = tr_read<v_rd_off(D0, 3, 1)>(vb); } while (0)
; #define PVMMA(OD, X) do { OD = __builtin_amdgcn_mfma_f32_32x32x16_bf16(pa0, PVPK(X[0], X[1]), OD, 0, 0, 0); OD = __builtin_amdgcn_mfma_f32_32x32x16_bf16(pa1, PVPK(X[2], X[3]), OD, 0, 0, 0); \
;     OD = __builtin_amdgcn_mfma_f32_32x32x16_bf16(pa2, PVPK(X[4], X[5]), OD, 0, 0, 0); OD = __builtin_amdgcn_mfma_f32_32x32x16_bf16(pa3, PVPK(X[6], X[7]), OD, 0, 0, 0); } while (0)
; #define PVWAIT() do { asm volatile("s_waitcnt lgkmcnt(0)" ::: "memory"); SBAR(); } while (0)
; #define PVEXP(P, B, N) do { _Pragma("unroll") for (int r = (B); r < (B) + (N); ++r) P[r] = __builtin_amdgcn_exp2f(P[r]); } while (0)
; __device__ __forceinline__ void expHalf(f32x16& p0) {
; #pragma unroll
;     for (int r = 0; r < 16; ++r) p0[r] = __builtin_amdgcn_exp2f(p0[r]);
; }
; __device__ __forceinline__ void finishSM(f32x16& p0, f32x16& p1, float& l_reg, bf16x8& pa0, bf16x8& pa1, bf16x8& pa2, bf16x8& pa3) {
;     float ps = 0;
; #pragma unroll
;     for (int r = 0; r < 16; ++r) ps += p0[r];
; #pragma unroll
;     for (int r = 0; r < 16; ++r) ps += p1[r];
;     l_reg += ps;
;     ...
;     PK4(p0, 0, pa0); PK4(p0, 8, pa1); PK4(p1, 0, pa2); PK4(p1, 8, pa3);
;     ...
; }
; template <int NB> __device__ __forceinline__ void pv_blocks(f32x16* o, int vb, bf16x8 pa0, bf16x8 pa1, bf16x8 pa2, bf16x8 pa3, f32x16& pe0, f32x16& pe1) {
;     s16x4 x[8], y[8];
;     ...
;     PVLOAD(0, x); PVWAIT();
;     if (NB == 4) {
;         PVLOAD(1, y); SBAR(); PVMMA(o[0], x); PVEXP(pe0, 0, 8); SBAR(); PVWAIT();
;         PVLOAD(2, x); SBAR(); PVMMA(o[1], y); PVEXP(pe0, 8, 8); SBAR(); PVWAIT();
;         PVLOAD(3, y); SBAR(); PVMMA(o[2], x); PVEXP(pe1, 0, 8); SBAR(); PVWAIT();
;         PVMMA(o[3], y); PVEXP(pe1, 8, 8);
;     } else {
;         PVLOAD(1, y); SBAR(); PVMMA(o[0], x); PVEXP(pe0, 0, 16); SBAR(); PVWAIT();
;         PVMMA(o[1], y); PVEXP(pe1, 0, 16);
;     }
;     ...
; }
.Lat_far_g1p:
	v_exp_f32_e32 v112, v112
	v_exp_f32_e32 v113, v113
	v_exp_f32_e32 v114, v114
	v_exp_f32_e32 v115, v115
	v_exp_f32_e32 v116, v116
	v_exp_f32_e32 v117, v117
	v_exp_f32_e32 v118, v118
	v_exp_f32_e32 v119, v119
	v_exp_f32_e32 v120, v120
	v_exp_f32_e32 v121, v121
	v_exp_f32_e32 v122, v122
	v_exp_f32_e32 v123, v123
	v_exp_f32_e32 v124, v124
	v_exp_f32_e32 v125, v125
	v_exp_f32_e32 v126, v126
	v_exp_f32_e32 v127, v127
	v_exp_f32_e32 v192, v192
	v_add_f32_e32 v64, v64, v112
	v_exp_f32_e32 v193, v193
	v_add_f32_e32 v65, v65, v113
	v_exp_f32_e32 v194, v194
	v_add_f32_e32 v66, v66, v114
	v_exp_f32_e32 v195, v195
	v_add_f32_e32 v67, v67, v115
	v_exp_f32_e32 v196, v196
	v_add_f32_e32 v64, v64, v116
	v_exp_f32_e32 v197, v197
	v_add_f32_e32 v65, v65, v117
	v_exp_f32_e32 v198, v198
	v_add_f32_e32 v66, v66, v118
	v_exp_f32_e32 v199, v199
	v_add_f32_e32 v67, v67, v119
	v_exp_f32_e32 v200, v200
	v_add_f32_e32 v64, v64, v120
	v_exp_f32_e32 v201, v201
	v_add_f32_e32 v65, v65, v121
	v_exp_f32_e32 v202, v202
	v_add_f32_e32 v66, v66, v122
	v_exp_f32_e32 v203, v203
	v_add_f32_e32 v67, v67, v123
	v_exp_f32_e32 v204, v204
	v_add_f32_e32 v64, v64, v124
	v_exp_f32_e32 v205, v205
	v_add_f32_e32 v65, v65, v125
	v_exp_f32_e32 v206, v206
	v_add_f32_e32 v66, v66, v126
	v_exp_f32_e32 v207, v207
	v_add_f32_e32 v67, v67, v127
	v_cvt_pk_bf16_f32 v208, v112, v113
	v_cvt_pk_bf16_f32 v209, v114, v115
	v_cvt_pk_bf16_f32 v210, v116, v117
	v_cvt_pk_bf16_f32 v211, v118, v119
	v_cvt_pk_bf16_f32 v212, v120, v121
	v_cvt_pk_bf16_f32 v213, v122, v123
	v_cvt_pk_bf16_f32 v214, v124, v125
	v_cvt_pk_bf16_f32 v215, v126, v127
	v_add_f32_e32 v64, v64, v192
	v_add_f32_e32 v65, v65, v193
	v_add_f32_e32 v66, v66, v194
	v_add_f32_e32 v67, v67, v195
	v_add_f32_e32 v64, v64, v196
	v_add_f32_e32 v65, v65, v197
	v_add_f32_e32 v66, v66, v198
	v_add_f32_e32 v67, v67, v199
	v_add_f32_e32 v64, v64, v200
	v_add_f32_e32 v65, v65, v201
	v_add_f32_e32 v66, v66, v202
	v_add_f32_e32 v67, v67, v203
	v_add_f32_e32 v64, v64, v204
	v_add_f32_e32 v65, v65, v205
	v_add_f32_e32 v66, v66, v206
	v_add_f32_e32 v67, v67, v207
	v_cvt_pk_bf16_f32 v216, v192, v193
	v_cvt_pk_bf16_f32 v217, v194, v195
	v_cvt_pk_bf16_f32 v218, v196, v197
	v_cvt_pk_bf16_f32 v219, v198, v199
	v_cvt_pk_bf16_f32 v220, v200, v201
	v_cvt_pk_bf16_f32 v221, v202, v203
	v_cvt_pk_bf16_f32 v222, v204, v205
	v_cvt_pk_bf16_f32 v223, v206, v207
	s_nop 1
	s_barrier
	s_setprio 0
	ds_read_b64_tr_b16 v[84:85], v168 offset:0
	ds_read_b64_tr_b16 v[86:87], v168 offset:2048
	ds_read_b64_tr_b16 v[88:89], v168 offset:4096
	ds_read_b64_tr_b16 v[90:91], v168 offset:6144
	ds_read_b64_tr_b16 v[92:93], v168 offset:8192
	ds_read_b64_tr_b16 v[94:95], v168 offset:10240
	ds_read_b64_tr_b16 v[128:129], v168 offset:12288
	ds_read_b64_tr_b16 v[130:131], v168 offset:14336
	ds_read_b64_tr_b16 v[132:133], v168 offset:512
	ds_read_b64_tr_b16 v[134:135], v168 offset:2560
	ds_read_b64_tr_b16 v[140:141], v168 offset:4608
	ds_read_b64_tr_b16 v[142:143], v168 offset:6656
	ds_read_b64_tr_b16 v[152:153], v168 offset:8704
	ds_read_b64_tr_b16 v[154:155], v168 offset:10752
	s_waitcnt lgkmcnt(12)
	v_mfma_f32_32x32x16_bf16 v[0:15], v[208:211], v[84:87], v[0:15]
	ds_read_b64_tr_b16 v[160:161], v168 offset:12800
	ds_read_b64_tr_b16 v[162:163], v168 offset:14848
	s_waitcnt lgkmcnt(12)
	v_mfma_f32_32x32x16_bf16 v[0:15], v[212:215], v[88:91], v[0:15]
	ds_read_b64_tr_b16 v[84:85], v168 offset:1024
	ds_read_b64_tr_b16 v[86:87], v168 offset:3072
	s_waitcnt lgkmcnt(12)
	v_mfma_f32_32x32x16_bf16 v[0:15], v[216:219], v[92:95], v[0:15]
	ds_read_b64_tr_b16 v[88:89], v168 offset:5120
	ds_read_b64_tr_b16 v[90:91], v168 offset:7168
	s_waitcnt lgkmcnt(12)
	v_mfma_f32_32x32x16_bf16 v[0:15], v[220:223], v[128:131], v[0:15]
	ds_read_b64_tr_b16 v[92:93], v168 offset:9216
	ds_read_b64_tr_b16 v[94:95], v168 offset:11264
	s_waitcnt lgkmcnt(12)
	v_mfma_f32_32x32x16_bf16 v[16:31], v[208:211], v[132:135], v[16:31]
	ds_read_b64_tr_b16 v[128:129], v168 offset:13312
	ds_read_b64_tr_b16 v[130:131], v168 offset:15360
	s_waitcnt lgkmcnt(12)
	v_mfma_f32_32x32x16_bf16 v[16:31], v[212:215], v[140:143], v[16:31]
	ds_read_b64_tr_b16 v[132:133], v168 offset:1536
	ds_read_b64_tr_b16 v[134:135], v168 offset:3584
	s_waitcnt lgkmcnt(12)
	v_mfma_f32_32x32x16_bf16 v[16:31], v[216:219], v[152:155], v[16:31]
	ds_read_b64_tr_b16 v[140:141], v168 offset:5632
	ds_read_b64_tr_b16 v[142:143], v168 offset:7680
	s_waitcnt lgkmcnt(12)
	v_mfma_f32_32x32x16_bf16 v[16:31], v[220:223], v[160:163], v[16:31]
	ds_read_b64_tr_b16 v[152:153], v168 offset:9728
	ds_read_b64_tr_b16 v[154:155], v168 offset:11776
	s_waitcnt lgkmcnt(12)
	v_mfma_f32_32x32x16_bf16 v[32:47], v[208:211], v[84:87], v[32:47]
	ds_read_b64_tr_b16 v[160:161], v168 offset:13824
	ds_read_b64_tr_b16 v[162:163], v168 offset:15872
	v_xor_b32_e32 v168, 0x4000, v168
	s_waitcnt lgkmcnt(12)
	v_mfma_f32_32x32x16_bf16 v[32:47], v[212:215], v[88:91], v[32:47]
	s_waitcnt lgkmcnt(10)
	v_mfma_f32_32x32x16_bf16 v[32:47], v[216:219], v[92:95], v[32:47]
	s_waitcnt lgkmcnt(8)
	v_mfma_f32_32x32x16_bf16 v[32:47], v[220:223], v[128:131], v[32:47]
	s_waitcnt lgkmcnt(6)
	v_mfma_f32_32x32x16_bf16 v[48:63], v[208:211], v[132:135], v[48:63]
	s_waitcnt lgkmcnt(4)
	v_mfma_f32_32x32x16_bf16 v[48:63], v[212:215], v[140:143], v[48:63]
	s_waitcnt lgkmcnt(2)
	v_mfma_f32_32x32x16_bf16 v[48:63], v[216:219], v[152:155], v[48:63]
	s_waitcnt lgkmcnt(0)
	v_mfma_f32_32x32x16_bf16 v[48:63], v[220:223], v[160:163], v[48:63]
	s_waitcnt vmcnt(0)
	s_barrier
